# qkv epilogue: next iteration's first-half rope rows prefetched after the current first half (on top of the both-halves-together loads)
# baseline (speedup 1.0000x reference)
.LBB0_241:
	ds_read_b128 v[0:3], v29
	ds_read_b128 v[4:7], v29 offset:16
	s_and_saveexec_b64 s[72:73], s[64:65]
	s_xor_b64 s[72:73], exec, s[72:73]
	s_or_saveexec_b64 s[72:73], s[72:73]
	v_add_u32_e32 v24, s78, v28
	v_add_u32_e32 v30, v29, v13
	s_xor_b64 exec, exec, s[72:73]
	s_cbranch_execz .LBB0_243
	s_cmp_lg_u32 s78, 0
	s_cbranch_scc1 .Lrope_steady
	v_lshrrev_b32_e32 v8, 6, v24
	v_cndmask_b32_e64 v8, v24, v8, s[46:47]
	v_lshlrev_b32_e32 v8, 6, v8
	v_and_b32_e32 v128, 0xfc0, v8
	v_lshl_add_u64 v[26:27], v[22:23], 0, v[128:129]
	global_load_dwordx4 v[158:161], v[26:27], off
	global_load_dwordx4 v[162:165], v[26:27], off offset:16
	v_lshl_add_u64 v[26:27], v[14:15], 0, v[128:129]
	global_load_dwordx4 v[166:169], v[26:27], off
	global_load_dwordx4 v[170:173], v[26:27], off offset:16
	v_add_u32_e32 v8, 8, v24
	v_lshrrev_b32_e32 v25, 6, v8
	v_cndmask_b32_e64 v8, v8, v25, s[46:47]
	v_lshlrev_b32_e32 v8, 6, v8
	v_and_b32_e32 v128, 0xfc0, v8
	v_lshl_add_u64 v[26:27], v[22:23], 0, v[128:129]
	global_load_dwordx4 v[142:145], v[26:27], off
	global_load_dwordx4 v[146:149], v[26:27], off offset:16
	v_lshl_add_u64 v[26:27], v[14:15], 0, v[128:129]
	global_load_dwordx4 v[150:153], v[26:27], off
	global_load_dwordx4 v[154:157], v[26:27], off offset:16
	ds_read_b128 v[36:39], v30
	ds_read_b128 v[48:51], v30 offset:16
	s_waitcnt vmcnt(7) lgkmcnt(1)
	v_mul_f32_e32 v8, v36, v158
	v_mul_f32_e32 v9, v37, v159
	v_mul_f32_e32 v10, v38, v160
	v_mul_f32_e32 v11, v39, v161
	s_waitcnt vmcnt(6) lgkmcnt(0)
	v_mul_f32_e32 v25, v48, v162
	v_mul_f32_e32 v26, v49, v163
	v_mul_f32_e32 v27, v50, v164
	v_mul_f32_e32 v31, v51, v165
	v_cndmask_b32_e64 v32, v8, -v8, s[48:49]
	v_cndmask_b32_e64 v33, v9, -v9, s[48:49]
	v_cndmask_b32_e64 v34, v10, -v10, s[48:49]
	v_cndmask_b32_e64 v35, v11, -v11, s[48:49]
	v_cndmask_b32_e64 v36, v25, -v25, s[48:49]
	v_cndmask_b32_e64 v37, v26, -v26, s[48:49]
	v_cndmask_b32_e64 v38, v27, -v27, s[48:49]
	v_cndmask_b32_e64 v39, v31, -v31, s[48:49]
	s_waitcnt vmcnt(5)
	v_fmac_f32_e32 v32, v0, v166
	v_fmac_f32_e32 v33, v1, v167
	v_fmac_f32_e32 v34, v2, v168
	v_fmac_f32_e32 v35, v3, v169
	s_waitcnt vmcnt(4)
	v_fmac_f32_e32 v36, v4, v170
	v_fmac_f32_e32 v37, v5, v171
	v_fmac_f32_e32 v38, v6, v172
	v_fmac_f32_e32 v39, v7, v173
	v_mov_b64_e32 v[0:1], v[32:33]
	v_mov_b64_e32 v[2:3], v[34:35]
	v_mov_b64_e32 v[4:5], v[36:37]
	v_mov_b64_e32 v[6:7], v[38:39]
	s_branch .Lrope_pfnext
.Lrope_steady:
	v_add_u32_e32 v8, 8, v24
	v_lshrrev_b32_e32 v25, 6, v8
	v_cndmask_b32_e64 v8, v8, v25, s[46:47]
	v_lshlrev_b32_e32 v8, 6, v8
	v_and_b32_e32 v128, 0xfc0, v8
	v_lshl_add_u64 v[26:27], v[22:23], 0, v[128:129]
	global_load_dwordx4 v[142:145], v[26:27], off
	global_load_dwordx4 v[146:149], v[26:27], off offset:16
	v_lshl_add_u64 v[26:27], v[14:15], 0, v[128:129]
	global_load_dwordx4 v[150:153], v[26:27], off
	global_load_dwordx4 v[154:157], v[26:27], off offset:16
	ds_read_b128 v[36:39], v30
	ds_read_b128 v[48:51], v30 offset:16
	s_waitcnt vmcnt(9) lgkmcnt(1)
	v_mul_f32_e32 v8, v36, v158
	v_mul_f32_e32 v9, v37, v159
	v_mul_f32_e32 v10, v38, v160
	v_mul_f32_e32 v11, v39, v161
	s_waitcnt vmcnt(8) lgkmcnt(0)
	v_mul_f32_e32 v25, v48, v162
	v_mul_f32_e32 v26, v49, v163
	v_mul_f32_e32 v27, v50, v164
	v_mul_f32_e32 v31, v51, v165
	v_cndmask_b32_e64 v32, v8, -v8, s[48:49]
	v_cndmask_b32_e64 v33, v9, -v9, s[48:49]
	v_cndmask_b32_e64 v34, v10, -v10, s[48:49]
	v_cndmask_b32_e64 v35, v11, -v11, s[48:49]
	v_cndmask_b32_e64 v36, v25, -v25, s[48:49]
	v_cndmask_b32_e64 v37, v26, -v26, s[48:49]
	v_cndmask_b32_e64 v38, v27, -v27, s[48:49]
	v_cndmask_b32_e64 v39, v31, -v31, s[48:49]
	s_waitcnt vmcnt(7)
	v_fmac_f32_e32 v32, v0, v166
	v_fmac_f32_e32 v33, v1, v167
	v_fmac_f32_e32 v34, v2, v168
	v_fmac_f32_e32 v35, v3, v169
	s_waitcnt vmcnt(6)
	v_fmac_f32_e32 v36, v4, v170
	v_fmac_f32_e32 v37, v5, v171
	v_fmac_f32_e32 v38, v6, v172
	v_fmac_f32_e32 v39, v7, v173
	v_mov_b64_e32 v[0:1], v[32:33]
	v_mov_b64_e32 v[2:3], v[34:35]
	v_mov_b64_e32 v[4:5], v[36:37]
	v_mov_b64_e32 v[6:7], v[38:39]
.Lrope_pfnext:
	v_add_u32_e32 v8, 16, v24
	v_lshrrev_b32_e32 v25, 6, v8
	v_cndmask_b32_e64 v8, v8, v25, s[46:47]
	v_lshlrev_b32_e32 v8, 6, v8
	v_and_b32_e32 v128, 0xfc0, v8
	v_lshl_add_u64 v[26:27], v[22:23], 0, v[128:129]
	global_load_dwordx4 v[158:161], v[26:27], off
	global_load_dwordx4 v[162:165], v[26:27], off offset:16
	v_lshl_add_u64 v[26:27], v[14:15], 0, v[128:129]
	global_load_dwordx4 v[166:169], v[26:27], off
	global_load_dwordx4 v[170:173], v[26:27], off offset:16

.LBB0_255:
	ds_read_b128 v[0:3], v29 offset:2176
	ds_read_b128 v[4:7], v29 offset:2192
	s_and_saveexec_b64 s[72:73], s[64:65]
	s_xor_b64 s[72:73], exec, s[72:73]
	s_or_saveexec_b64 s[72:73], s[72:73]
	v_add_u32_e32 v24, 8, v24
	s_xor_b64 exec, exec, s[72:73]
	s_cbranch_execz .LBB0_259
	ds_read_b128 v[46:49], v30 offset:2176
	ds_read_b128 v[50:53], v30 offset:2192
	s_waitcnt vmcnt(8) lgkmcnt(1)
	v_mul_f32_e32 v8, v46, v142
	v_mul_f32_e32 v9, v47, v143
	v_mul_f32_e32 v10, v48, v144
	v_mul_f32_e32 v11, v49, v145
	s_waitcnt vmcnt(7) lgkmcnt(0)
	v_mul_f32_e32 v25, v50, v146
	v_mul_f32_e32 v26, v51, v147
	v_mul_f32_e32 v27, v52, v148
	v_mul_f32_e32 v37, v53, v149
	v_cndmask_b32_e64 v30, v8, -v8, s[48:49]
	v_cndmask_b32_e64 v31, v9, -v9, s[48:49]
	v_cndmask_b32_e64 v32, v10, -v10, s[48:49]
	v_cndmask_b32_e64 v33, v11, -v11, s[48:49]
	v_cndmask_b32_e64 v34, v25, -v25, s[48:49]
	v_cndmask_b32_e64 v35, v26, -v26, s[48:49]
	v_cndmask_b32_e64 v36, v27, -v27, s[48:49]
	v_cndmask_b32_e64 v37, v37, -v37, s[48:49]
	s_waitcnt vmcnt(6)
	v_fmac_f32_e32 v30, v0, v150
	v_fmac_f32_e32 v31, v1, v151
	v_fmac_f32_e32 v32, v2, v152
	v_fmac_f32_e32 v33, v3, v153
	s_waitcnt vmcnt(5)
	v_fmac_f32_e32 v34, v4, v154
	v_fmac_f32_e32 v35, v5, v155
	v_fmac_f32_e32 v36, v6, v156
	v_fmac_f32_e32 v37, v7, v157
	v_mov_b64_e32 v[0:1], v[30:31]
	v_mov_b64_e32 v[2:3], v[32:33]
	v_mov_b64_e32 v[4:5], v[34:35]
	v_mov_b64_e32 v[6:7], v[36:37]
